# grid barrier: the first arriver of each XCD starts an early L2 writeback (not waited for) so the leader's writeback finds a cleaner L2
# baseline (speedup 1.0000x reference)
; __device__ __forceinline__ unsigned xb_ld(unsigned* p)              { return __hip_atomic_load(p, __ATOMIC_RELAXED, __HIP_MEMORY_SCOPE_AGENT); }
; __device__ __forceinline__ unsigned xb_add(unsigned* p, unsigned v) { return __hip_atomic_fetch_add(p, v, __ATOMIC_RELAXED, __HIP_MEMORY_SCOPE_AGENT); }
; #define XB_SPIN(cond, bar) do { unsigned _sp = 0; while (cond) { __builtin_amdgcn_s_sleep(1); \
;     if ((++_sp & 255u) == 0u) { if (xb_ld(&(bar)[XB_TMO])) break; if (_sp > XB_SPIN_CAP) { atomicAdd(&(bar)[XB_TMO], 1u); break; } } } } while (0)
; __device__ __forceinline__ void xcd_barrier(const XcdBarrier& b) {
;     ...
;         const unsigned old = xb_add(&bar[XB_XSUB(b.x)], 1u);
;         const unsigned gen = old / nloc;
;         if (old + 1u == (gen + 1u) * nloc) {
;             __builtin_amdgcn_fence(__ATOMIC_RELEASE, "agent");
;     ...
;             XB_SPIN(xb_ld(&bar[XB_XGEN(b.x)]) == gen, bar);
.LBB0_134:
	v_readlane_b32 s4, v254, 9
	s_lshl_b32 s4, s4, 8
	v_readlane_b32 s6, v254, 7
	v_readlane_b32 s7, v254, 8
	s_add_u32 s4, s6, s4
	s_addc_u32 s5, s7, 0
	v_mov_b32_e32 v2, 0x1000
	v_mov_b32_e32 v4, 1
	global_atomic_add v4, v2, v4, s[4:5] offset:1024 sc0
	v_cvt_f32_u32_e32 v2, v3
	v_sub_u32_e32 v5, 0, v3
	v_rcp_iflag_f32_e32 v2, v2
	s_nop 0
	v_mul_f32_e32 v2, 0x4f7ffffe, v2
	v_cvt_u32_f32_e32 v2, v2
	v_mul_lo_u32 v5, v5, v2
	v_mul_hi_u32 v5, v2, v5
	v_add_u32_e32 v2, v2, v5
	s_waitcnt vmcnt(0)
	v_mul_hi_u32 v2, v4, v2
	v_mul_lo_u32 v5, v2, v3
	v_sub_u32_e32 v5, v4, v5
	v_add_u32_e32 v6, 1, v2
	v_cmp_ge_u32_e32 vcc, v5, v3
	v_add_u32_e32 v4, 1, v4
	s_nop 0
	v_cndmask_b32_e32 v2, v2, v6, vcc
	v_sub_u32_e32 v6, v5, v3
	v_cndmask_b32_e32 v5, v5, v6, vcc
	v_add_u32_e32 v6, 1, v2
	v_cmp_ge_u32_e32 vcc, v5, v3
	s_nop 1
	v_cndmask_b32_e32 v2, v2, v6, vcc
	v_mul_lo_u32 v5, v3, v2
	v_add_u32_e32 v3, v5, v3
	v_cmp_ne_u32_e32 vcc, v4, v3
	s_and_saveexec_b64 s[6:7], vcc
	s_xor_b64 s[6:7], exec, s[6:7]
	s_cbranch_execz .LBB0_148
	s_waitcnt lgkmcnt(0)
	v_sub_u32_e32 v12, v4, v5
	v_sub_u32_e32 v13, v3, v5
	v_cmp_eq_u32_e32 vcc, 1, v12
	s_cbranch_vccnz .Lbwf_1
	s_branch .Lbwn_1
.Lbwf_1:
	buffer_wbl2 sc1
.Lbwn_1:
	v_readlane_b32 s10, v254, 7
	v_readlane_b32 s11, v254, 8
	v_mov_b32_e32 v1, 0
	s_add_u32 s10, s10, 0x3500
	s_addc_u32 s11, s11, 0
	s_mov_b64 s[8:9], exec
	s_mov_b32 s22, 0
	global_load_dword v10, v1, s[10:11] sc1

; __device__ __forceinline__ unsigned xb_add(unsigned* p, unsigned v) { return __hip_atomic_fetch_add(p, v, __ATOMIC_RELAXED, __HIP_MEMORY_SCOPE_AGENT); }
; __device__ __forceinline__ void xcd_barrier(const XcdBarrier& b) {
;     ...
;         const unsigned old = xb_add(&bar[XB_XSUB(b.x)], 1u);
;         const unsigned gen = old / nloc;
;         if (old + 1u == (gen + 1u) * nloc) {
;             __builtin_amdgcn_fence(__ATOMIC_RELEASE, "agent");
.LBB0_3529:
	v_readlane_b32 s4, v254, 9
	s_lshl_b32 s4, s4, 8
	v_readlane_b32 s6, v254, 7
	v_readlane_b32 s7, v254, 8
	s_add_u32 s4, s6, s4
	s_addc_u32 s5, s7, 0
	v_mov_b32_e32 v1, 0x1000
	v_mov_b32_e32 v3, 1
	global_atomic_add v3, v1, v3, s[4:5] offset:1024 sc0
	v_cvt_f32_u32_e32 v1, v2
	v_sub_u32_e32 v4, 0, v2
	v_rcp_iflag_f32_e32 v1, v1
	s_nop 0
	v_mul_f32_e32 v1, 0x4f7ffffe, v1
	v_cvt_u32_f32_e32 v1, v1
	v_mul_lo_u32 v4, v4, v1
	v_mul_hi_u32 v4, v1, v4
	v_add_u32_e32 v1, v1, v4
	s_waitcnt vmcnt(0)
	v_mul_hi_u32 v1, v3, v1
	v_mul_lo_u32 v4, v1, v2
	v_sub_u32_e32 v4, v3, v4
	v_add_u32_e32 v5, 1, v1
	v_cmp_ge_u32_e32 vcc, v4, v2
	v_add_u32_e32 v3, 1, v3
	s_nop 0
	v_cndmask_b32_e32 v1, v1, v5, vcc
	v_sub_u32_e32 v5, v4, v2
	v_cndmask_b32_e32 v4, v4, v5, vcc
	v_add_u32_e32 v5, 1, v1
	v_cmp_ge_u32_e32 vcc, v4, v2
	s_nop 1
	v_cndmask_b32_e32 v1, v1, v5, vcc
	v_mul_lo_u32 v4, v2, v1
	v_add_u32_e32 v2, v4, v2
	v_cmp_ne_u32_e32 vcc, v3, v2
	s_and_saveexec_b64 s[6:7], vcc
	s_xor_b64 s[6:7], exec, s[6:7]
	s_cbranch_execz .LBB0_3543
	s_waitcnt lgkmcnt(0)
	v_sub_u32_e32 v12, v3, v4
	v_sub_u32_e32 v13, v2, v4
	v_cmp_eq_u32_e32 vcc, 1, v12
	s_cbranch_vccnz .Lbwf_22
	s_branch .Lbwn_22

; __device__ __forceinline__ unsigned xb_ld(unsigned* p)              { return __hip_atomic_load(p, __ATOMIC_RELAXED, __HIP_MEMORY_SCOPE_AGENT); }
; #define XB_SPIN(cond, bar) do { unsigned _sp = 0; while (cond) { __builtin_amdgcn_s_sleep(1); \
;     if ((++_sp & 255u) == 0u) { if (xb_ld(&(bar)[XB_TMO])) break; if (_sp > XB_SPIN_CAP) { atomicAdd(&(bar)[XB_TMO], 1u); break; } } } } while (0)
; __device__ __forceinline__ void xcd_barrier(const XcdBarrier& b) {
;     ...
;         } else {
;             XB_SPIN(xb_ld(&bar[XB_XGEN(b.x)]) == gen, bar);
.Lbwn_22:
	v_readlane_b32 s10, v254, 7
	v_readlane_b32 s11, v254, 8
	v_mov_b32_e32 v0, 0
	s_add_u32 s10, s10, 0x3500
	s_addc_u32 s11, s11, 0
	s_mov_b64 s[8:9], exec
	s_mov_b32 s22, 0
	global_load_dword v10, v0, s[10:11] sc1
